# v26 + EpiGateB second half-tile gate loads issued with the first half-tile's (one exposed load latency per o_b unit)
# speedup vs baseline: 1.0098x; 1.0090x over previous
; __device__ __forceinline__ unsigned pk_bf16(float lo, float hi) { typedef __bf16 b2 __attribute__((ext_vector_type(2))); f32x2 v = {lo, hi}; b2 b = __builtin_convertvector(v, b2); return __builtin_bit_cast(unsigned, b); }
; __device__ __forceinline__ float bflo(unsigned u) { return __uint_as_float(u << 16); }
; __device__ __forceinline__ float bfhi(unsigned u) { return __uint_as_float(u & 0xffff0000u); }
;     __device__ __forceinline__ void operator()(const f32x4 (&acc)[2][2][4][2], const Unit& u, int wr, int wc, int fr, int fq) const {
;         const int row0 = u.pm * 256 + wr * 64 + fr, col0 = u.pn * 256 + wc * 32 + 8 * fq;
; #pragma unroll
;         for (int ai = 0; ai < 2; ++ai) { u32x4 gg[4][2];
; #pragma unroll
;             for (int m = 0; m < 4; ++m)
; #pragma unroll
;                 for (int bj = 0; bj < 2; ++bj) gg[m][bj] = *(const u32x4*)(gates + (size_t)(row0 + ai * 128 + m * 16) * 2048 + 1024 + col0 + bj * 128);
; #pragma unroll
;             for (int m = 0; m < 4; ++m) { const size_t row = row0 + ai * 128 + m * 16;
; #pragma unroll
;                 for (int bj = 0; bj < 2; ++bj) { const int col = col0 + bj * 128; const u32x4 g = gg[m][bj];
;                     const f32x4 v0 = acc[ai][bj][m][0], v1 = acc[ai][bj][m][1]; u32x4 w;
;                     w.x = pk_bf16(v0[0] * bflo(g.x), v0[1] * bfhi(g.x)); w.y = pk_bf16(v0[2] * bflo(g.y), v0[3] * bfhi(g.y));
;                     w.z = pk_bf16(v1[0] * bflo(g.z), v1[1] * bfhi(g.z)); w.w = pk_bf16(v1[2] * bflo(g.w), v1[3] * bfhi(g.w));
;                     *(u32x4*)(tmpb + row * 1024 + col) = w; } } }
.LBB0_487:
	v_lshl_add_u32 v136, s46, 8, v146
	v_lshlrev_b64 v[142:143], 12, v[136:137]
	v_lshl_add_u64 v[144:145], s[0:1], 0, v[142:143]
	v_lshl_or_b32 v142, s45, 9, v151
	v_mov_b32_e32 v143, v137
	v_lshl_add_u64 v[144:145], v[144:145], 0, v[142:143]
	v_mov_b32_e32 v175, v137
	v_or_b32_e32 v174, 16, v136
	global_load_dwordx4 v[154:157], v[144:145], off offset:2048
	global_load_dwordx4 v[158:161], v[144:145], off offset:2304
	v_lshlrev_b64 v[144:145], 12, v[174:175]
	v_lshl_add_u64 v[144:145], s[0:1], 0, v[144:145]
	v_lshl_add_u64 v[144:145], v[144:145], 0, v[142:143]
	global_load_dwordx4 v[162:165], v[144:145], off offset:2048
	global_load_dwordx4 v[166:169], v[144:145], off offset:2304
	v_mov_b32_e32 v187, v137
	v_or_b32_e32 v186, 32, v136
	v_lshlrev_b64 v[170:171], 12, v[186:187]
	v_lshl_add_u64 v[170:171], s[0:1], 0, v[170:171]
	v_lshl_add_u64 v[180:181], v[170:171], 0, v[142:143]
	global_load_dwordx4 v[170:173], v[180:181], off offset:2048
	v_mov_b32_e32 v145, v137
	v_or_b32_e32 v144, 48, v136
	v_lshlrev_b64 v[178:179], 12, v[144:145]
	v_lshlrev_b64 v[176:177], 11, v[136:137]
	v_lshlrev_b64 v[174:175], 11, v[174:175]
	v_lshl_add_u64 v[178:179], s[0:1], 0, v[178:179]
	v_lshl_add_u64 v[176:177], s[4:5], 0, v[176:177]
	v_lshl_add_u64 v[174:175], s[4:5], 0, v[174:175]
	v_lshl_add_u64 v[182:183], v[178:179], 0, v[142:143]
	v_lshl_add_u64 v[190:191], v[176:177], 0, v[142:143]
	v_lshl_add_u64 v[192:193], v[174:175], 0, v[142:143]
	global_load_dwordx4 v[174:177], v[180:181], off offset:2304
	s_nop 0
	global_load_dwordx4 v[178:181], v[182:183], off offset:2048
	s_nop 0
	global_load_dwordx4 v[182:185], v[182:183], off offset:2304
	v_add_u32_e32 v236, 0x80, v136
	v_mov_b32_e32 v237, v137
	v_lshlrev_b64 v[236:237], 12, v[236:237]
	v_lshl_add_u64 v[236:237], s[0:1], 0, v[236:237]
	v_lshl_add_u64 v[236:237], v[236:237], 0, v[142:143]
	global_load_dwordx4 v[204:207], v[236:237], off offset:2048
	global_load_dwordx4 v[208:211], v[236:237], off offset:2304
	v_add_u32_e32 v236, 0x90, v136
	v_mov_b32_e32 v237, v137
	v_lshlrev_b64 v[236:237], 12, v[236:237]
	v_lshl_add_u64 v[236:237], s[0:1], 0, v[236:237]
	v_lshl_add_u64 v[236:237], v[236:237], 0, v[142:143]
	global_load_dwordx4 v[212:215], v[236:237], off offset:2048
	global_load_dwordx4 v[216:219], v[236:237], off offset:2304
	v_add_u32_e32 v236, 0xa0, v136
	v_mov_b32_e32 v237, v137
	v_lshlrev_b64 v[236:237], 12, v[236:237]
	v_lshl_add_u64 v[236:237], s[0:1], 0, v[236:237]
	v_lshl_add_u64 v[236:237], v[236:237], 0, v[142:143]
	global_load_dwordx4 v[220:223], v[236:237], off offset:2048
	global_load_dwordx4 v[224:227], v[236:237], off offset:2304
	v_add_u32_e32 v236, 0xb0, v136
	v_mov_b32_e32 v237, v137
	v_lshlrev_b64 v[236:237], 12, v[236:237]
	v_lshl_add_u64 v[236:237], s[0:1], 0, v[236:237]
	v_lshl_add_u64 v[236:237], v[236:237], 0, v[142:143]
	global_load_dwordx4 v[228:231], v[236:237], off offset:2048
	global_load_dwordx4 v[232:235], v[236:237], off offset:2304
	s_andn2_b64 vcc, exec, s[16:17]
	s_mov_b64 s[16:17], -1
	s_waitcnt vmcnt(8)
	v_lshlrev_b32_e32 v194, 16, v154
	v_and_b32_e32 v195, 0xffff0000, v154
	v_lshlrev_b32_e32 v154, 16, v155
	v_and_b32_e32 v155, 0xffff0000, v155
	v_lshlrev_b32_e32 v196, 16, v156
	v_and_b32_e32 v197, 0xffff0000, v156
	v_lshlrev_b32_e32 v156, 16, v157
	v_and_b32_e32 v157, 0xffff0000, v157
	v_lshlrev_b32_e32 v198, 16, v158
	v_and_b32_e32 v199, 0xffff0000, v158
	v_lshlrev_b32_e32 v158, 16, v159
	v_and_b32_e32 v159, 0xffff0000, v159
	v_lshlrev_b32_e32 v200, 16, v160
	v_and_b32_e32 v201, 0xffff0000, v160
	v_lshlrev_b32_e32 v160, 16, v161
	v_and_b32_e32 v161, 0xffff0000, v161
	v_pk_mul_f32 v[124:125], v[124:125], v[194:195]
	v_pk_mul_f32 v[126:127], v[126:127], v[154:155]
	v_pk_mul_f32 v[120:121], v[120:121], v[196:197]
	v_pk_mul_f32 v[122:123], v[122:123], v[156:157]
	v_pk_mul_f32 v[114:115], v[114:115], v[158:159]
	v_pk_mul_f32 v[156:157], v[106:107], v[160:161]
	v_lshlrev_b32_e32 v158, 16, v162
	v_and_b32_e32 v159, 0xffff0000, v162
	v_lshlrev_b32_e32 v160, 16, v163
	v_and_b32_e32 v161, 0xffff0000, v163
	v_lshlrev_b32_e32 v162, 16, v164
	v_and_b32_e32 v163, 0xffff0000, v164
	v_lshlrev_b32_e32 v164, 16, v165
	v_and_b32_e32 v165, 0xffff0000, v165
	v_pk_mul_f32 v[112:113], v[112:113], v[198:199]
	v_pk_mul_f32 v[154:155], v[104:105], v[200:201]
	v_cvt_pk_bf16_f32 v104, v124, v125
	v_cvt_pk_bf16_f32 v105, v126, v127
	v_cvt_pk_bf16_f32 v106, v120, v121
	v_cvt_pk_bf16_f32 v107, v122, v123
	v_pk_mul_f32 v[116:117], v[116:117], v[158:159]
	v_pk_mul_f32 v[118:119], v[118:119], v[160:161]
	v_pk_mul_f32 v[108:109], v[108:109], v[162:163]
	v_pk_mul_f32 v[110:111], v[110:111], v[164:165]
	v_cvt_pk_bf16_f32 v112, v112, v113
	v_cvt_pk_bf16_f32 v113, v114, v115
	v_cvt_pk_bf16_f32 v114, v154, v155
	v_cvt_pk_bf16_f32 v115, v156, v157
	global_store_dwordx4 v[190:191], v[104:107], off
	global_store_dwordx4 v[190:191], v[112:115], off offset:256
	v_lshlrev_b32_e32 v194, 16, v166
	v_cvt_pk_bf16_f32 v104, v116, v117
	v_cvt_pk_bf16_f32 v105, v118, v119
	v_cvt_pk_bf16_f32 v106, v108, v109
	v_cvt_pk_bf16_f32 v107, v110, v111
	v_and_b32_e32 v195, 0xffff0000, v166
	global_store_dwordx4 v[192:193], v[104:107], off
	v_pk_mul_f32 v[100:101], v[100:101], v[194:195]
	s_nop 0
	v_lshlrev_b32_e32 v104, 16, v167
	v_and_b32_e32 v105, 0xffff0000, v167
	v_pk_mul_f32 v[102:103], v[102:103], v[104:105]
	v_cvt_pk_bf16_f32 v100, v100, v101
	v_cvt_pk_bf16_f32 v101, v102, v103
	v_lshlrev_b32_e32 v102, 16, v168
	v_and_b32_e32 v103, 0xffff0000, v168
	v_pk_mul_f32 v[92:93], v[92:93], v[102:103]
	s_nop 0
	v_cvt_pk_bf16_f32 v102, v92, v93
	v_lshlrev_b32_e32 v92, 16, v169
	v_and_b32_e32 v93, 0xffff0000, v169
; __device__ __forceinline__ unsigned pk_bf16(float lo, float hi) { typedef __bf16 b2 __attribute__((ext_vector_type(2))); f32x2 v = {lo, hi}; b2 b = __builtin_convertvector(v, b2); return __builtin_bit_cast(unsigned, b); }
; __device__ __forceinline__ float bflo(unsigned u) { return __uint_as_float(u << 16); }
; __device__ __forceinline__ float bfhi(unsigned u) { return __uint_as_float(u & 0xffff0000u); }
;     __device__ __forceinline__ void operator()(const f32x4 (&acc)[2][2][4][2], const Unit& u, int wr, int wc, int fr, int fq) const {
;     ...
;             for (int m = 0; m < 4; ++m) { const size_t row = row0 + ai * 128 + m * 16;
; #pragma unroll
;                 for (int bj = 0; bj < 2; ++bj) { const int col = col0 + bj * 128; const u32x4 g = gg[m][bj];
;                     const f32x4 v0 = acc[ai][bj][m][0], v1 = acc[ai][bj][m][1]; u32x4 w;
;                     w.x = pk_bf16(v0[0] * bflo(g.x), v0[1] * bfhi(g.x)); w.y = pk_bf16(v0[2] * bflo(g.y), v0[3] * bfhi(g.y));
;                     w.z = pk_bf16(v1[0] * bflo(g.z), v1[1] * bfhi(g.z)); w.w = pk_bf16(v1[2] * bflo(g.w), v1[3] * bfhi(g.w));
;                     *(u32x4*)(tmpb + row * 1024 + col) = w; } } }
	v_pk_mul_f32 v[92:93], v[94:95], v[92:93]
	v_lshlrev_b32_e32 v94, 16, v171
	v_cvt_pk_bf16_f32 v103, v92, v93
	v_lshlrev_b32_e32 v92, 16, v170
	v_and_b32_e32 v93, 0xffff0000, v170
	v_and_b32_e32 v95, 0xffff0000, v171
	v_pk_mul_f32 v[92:93], v[96:97], v[92:93]
	v_pk_mul_f32 v[94:95], v[98:99], v[94:95]
	v_cvt_pk_bf16_f32 v92, v92, v93
	v_cvt_pk_bf16_f32 v93, v94, v95
	v_lshlrev_b32_e32 v94, 16, v172
	v_and_b32_e32 v95, 0xffff0000, v172
	v_pk_mul_f32 v[88:89], v[88:89], v[94:95]
	global_store_dwordx4 v[192:193], v[100:103], off offset:256
	v_cvt_pk_bf16_f32 v94, v88, v89
	v_lshlrev_b32_e32 v88, 16, v173
	v_and_b32_e32 v89, 0xffff0000, v173
	v_pk_mul_f32 v[88:89], v[90:91], v[88:89]
	v_lshlrev_b32_e32 v90, 16, v174
	v_and_b32_e32 v91, 0xffff0000, v174
	v_pk_mul_f32 v[84:85], v[84:85], v[90:91]
	v_lshlrev_b32_e32 v90, 16, v175
	v_and_b32_e32 v91, 0xffff0000, v175
	v_pk_mul_f32 v[86:87], v[86:87], v[90:91]
	v_cvt_pk_bf16_f32 v84, v84, v85
	v_cvt_pk_bf16_f32 v85, v86, v87
	v_lshlrev_b32_e32 v86, 16, v176
	v_and_b32_e32 v87, 0xffff0000, v176
	v_pk_mul_f32 v[76:77], v[76:77], v[86:87]
	v_lshlrev_b64 v[100:101], 11, v[186:187]
	v_cvt_pk_bf16_f32 v86, v76, v77
	v_lshlrev_b32_e32 v76, 16, v177
	v_and_b32_e32 v77, 0xffff0000, v177
	v_pk_mul_f32 v[76:77], v[78:79], v[76:77]
	v_lshlrev_b32_e32 v78, 16, v179
	v_cvt_pk_bf16_f32 v87, v76, v77
	v_lshlrev_b32_e32 v76, 16, v178
	v_and_b32_e32 v77, 0xffff0000, v178
	v_and_b32_e32 v79, 0xffff0000, v179
	v_pk_mul_f32 v[76:77], v[80:81], v[76:77]
	v_pk_mul_f32 v[78:79], v[82:83], v[78:79]
	v_cvt_pk_bf16_f32 v76, v76, v77
	v_cvt_pk_bf16_f32 v77, v78, v79
	v_lshlrev_b32_e32 v78, 16, v180
	v_and_b32_e32 v79, 0xffff0000, v180
	v_pk_mul_f32 v[72:73], v[72:73], v[78:79]
	v_cvt_pk_bf16_f32 v95, v88, v89
	v_cvt_pk_bf16_f32 v78, v72, v73
	v_lshlrev_b32_e32 v72, 16, v181
	v_and_b32_e32 v73, 0xffff0000, v181
	v_pk_mul_f32 v[72:73], v[74:75], v[72:73]
	v_lshlrev_b32_e32 v74, 16, v182
	v_and_b32_e32 v75, 0xffff0000, v182
	v_pk_mul_f32 v[68:69], v[68:69], v[74:75]
	v_lshlrev_b32_e32 v74, 16, v183
	v_and_b32_e32 v75, 0xffff0000, v183
	v_pk_mul_f32 v[70:71], v[70:71], v[74:75]
	v_cvt_pk_bf16_f32 v68, v68, v69
	v_cvt_pk_bf16_f32 v69, v70, v71
	v_lshlrev_b32_e32 v70, 16, v184
	v_and_b32_e32 v71, 0xffff0000, v184
	v_lshl_add_u64 v[88:89], s[4:5], 0, v[100:101]
	v_pk_mul_f32 v[64:65], v[64:65], v[70:71]
	v_lshl_add_u64 v[88:89], v[88:89], 0, v[142:143]
	v_cvt_pk_bf16_f32 v70, v64, v65
	v_lshlrev_b32_e32 v64, 16, v185
	v_and_b32_e32 v65, 0xffff0000, v185
	global_store_dwordx4 v[88:89], v[84:87], off offset:256
	v_pk_mul_f32 v[64:65], v[66:67], v[64:65]
	v_add_u32_e32 v96, 0x80, v136
	v_lshlrev_b64 v[84:85], 11, v[144:145]
	v_mov_b32_e32 v97, v137
	v_cvt_pk_bf16_f32 v79, v72, v73
	v_lshl_add_u64 v[72:73], s[4:5], 0, v[84:85]
	v_cvt_pk_bf16_f32 v71, v64, v65
	v_lshlrev_b64 v[64:65], 12, v[96:97]
	v_lshl_add_u64 v[72:73], v[72:73], 0, v[142:143]
	v_lshl_add_u64 v[64:65], s[0:1], 0, v[64:65]
	global_store_dwordx4 v[88:89], v[92:95], off
	global_store_dwordx4 v[72:73], v[76:79], off
	global_store_dwordx4 v[72:73], v[68:71], off offset:256
	v_lshl_add_u64 v[64:65], v[64:65], 0, v[142:143]
	v_add_u32_e32 v98, 0x90, v136
	v_mov_b32_e32 v99, v137
	v_lshlrev_b64 v[64:65], 12, v[98:99]
	v_lshl_add_u64 v[64:65], s[0:1], 0, v[64:65]
	v_lshl_add_u64 v[64:65], v[64:65], 0, v[142:143]
	v_add_u32_e32 v100, 0xa0, v136
	v_mov_b32_e32 v101, v137
	v_lshlrev_b64 v[64:65], 12, v[100:101]
	v_lshl_add_u64 v[64:65], s[0:1], 0, v[64:65]
	v_lshl_add_u64 v[64:65], v[64:65], 0, v[142:143]
	v_add_u32_e32 v136, 0xb0, v136
	v_lshlrev_b64 v[64:65], 12, v[136:137]
	v_lshl_add_u64 v[64:65], s[0:1], 0, v[64:65]
	v_lshl_add_u64 v[64:65], v[64:65], 0, v[142:143]
	s_nop 0
	v_lshlrev_b64 v[96:97], 11, v[96:97]
	s_waitcnt vmcnt(15)
	v_lshlrev_b32_e32 v102, 16, v204
	v_and_b32_e32 v103, 0xffff0000, v204
	v_lshlrev_b32_e32 v68, 16, v205
	v_and_b32_e32 v69, 0xffff0000, v205
	v_pk_mul_f32 v[60:61], v[60:61], v[102:103]
	v_pk_mul_f32 v[62:63], v[62:63], v[68:69]
	v_cvt_pk_bf16_f32 v60, v60, v61
	v_cvt_pk_bf16_f32 v61, v62, v63
	v_lshlrev_b32_e32 v62, 16, v206
	v_and_b32_e32 v63, 0xffff0000, v206
	v_pk_mul_f32 v[56:57], v[56:57], v[62:63]
	s_nop 0
	v_cvt_pk_bf16_f32 v62, v56, v57
	v_lshlrev_b32_e32 v56, 16, v207
	v_and_b32_e32 v57, 0xffff0000, v207
	v_pk_mul_f32 v[56:57], v[58:59], v[56:57]
	s_waitcnt vmcnt(14)
	v_lshlrev_b32_e32 v58, 16, v208
	v_and_b32_e32 v59, 0xffff0000, v208
	v_pk_mul_f32 v[52:53], v[52:53], v[58:59]
	v_lshlrev_b32_e32 v58, 16, v209
	v_and_b32_e32 v59, 0xffff0000, v209
	v_pk_mul_f32 v[54:55], v[54:55], v[58:59]
	v_cvt_pk_bf16_f32 v52, v52, v53
	v_cvt_pk_bf16_f32 v53, v54, v55
	v_lshlrev_b32_e32 v54, 16, v210
	v_and_b32_e32 v55, 0xffff0000, v210
	v_pk_mul_f32 v[44:45], v[44:45], v[54:55]
	v_cvt_pk_bf16_f32 v63, v56, v57
	v_cvt_pk_bf16_f32 v54, v44, v45
	v_lshlrev_b32_e32 v44, 16, v211
	v_and_b32_e32 v45, 0xffff0000, v211
	v_pk_mul_f32 v[44:45], v[46:47], v[44:45]
	s_waitcnt vmcnt(13)
; __device__ __forceinline__ unsigned pk_bf16(float lo, float hi) { typedef __bf16 b2 __attribute__((ext_vector_type(2))); f32x2 v = {lo, hi}; b2 b = __builtin_convertvector(v, b2); return __builtin_bit_cast(unsigned, b); }
; __device__ __forceinline__ float bflo(unsigned u) { return __uint_as_float(u << 16); }
; __device__ __forceinline__ float bfhi(unsigned u) { return __uint_as_float(u & 0xffff0000u); }
;     __device__ __forceinline__ void operator()(const f32x4 (&acc)[2][2][4][2], const Unit& u, int wr, int wc, int fr, int fq) const {
;     ...
;             for (int m = 0; m < 4; ++m) { const size_t row = row0 + ai * 128 + m * 16;
; #pragma unroll
;                 for (int bj = 0; bj < 2; ++bj) { const int col = col0 + bj * 128; const u32x4 g = gg[m][bj];
;                     const f32x4 v0 = acc[ai][bj][m][0], v1 = acc[ai][bj][m][1]; u32x4 w;
;                     w.x = pk_bf16(v0[0] * bflo(g.x), v0[1] * bfhi(g.x)); w.y = pk_bf16(v0[2] * bflo(g.y), v0[3] * bfhi(g.y));
;                     w.z = pk_bf16(v1[0] * bflo(g.z), v1[1] * bfhi(g.z)); w.w = pk_bf16(v1[2] * bflo(g.w), v1[3] * bfhi(g.w));
;                     *(u32x4*)(tmpb + row * 1024 + col) = w; } } }
	v_lshlrev_b32_e32 v46, 16, v213
	v_cvt_pk_bf16_f32 v55, v44, v45
	v_lshlrev_b32_e32 v44, 16, v212
	v_and_b32_e32 v45, 0xffff0000, v212
	v_and_b32_e32 v47, 0xffff0000, v213
	v_pk_mul_f32 v[44:45], v[48:49], v[44:45]
	v_pk_mul_f32 v[46:47], v[50:51], v[46:47]
	v_cvt_pk_bf16_f32 v44, v44, v45
	v_cvt_pk_bf16_f32 v45, v46, v47
	v_lshlrev_b32_e32 v46, 16, v214
	v_and_b32_e32 v47, 0xffff0000, v214
	v_pk_mul_f32 v[40:41], v[40:41], v[46:47]
	v_lshl_add_u64 v[56:57], s[4:5], 0, v[96:97]
	v_cvt_pk_bf16_f32 v46, v40, v41
	v_lshlrev_b32_e32 v40, 16, v215
	v_and_b32_e32 v41, 0xffff0000, v215
	v_pk_mul_f32 v[40:41], v[42:43], v[40:41]
	s_waitcnt vmcnt(12)
	v_lshlrev_b32_e32 v42, 16, v216
	v_and_b32_e32 v43, 0xffff0000, v216
	v_pk_mul_f32 v[36:37], v[36:37], v[42:43]
	v_lshlrev_b32_e32 v42, 16, v217
	v_and_b32_e32 v43, 0xffff0000, v217
	v_pk_mul_f32 v[38:39], v[38:39], v[42:43]
	v_cvt_pk_bf16_f32 v36, v36, v37
	v_cvt_pk_bf16_f32 v37, v38, v39
	v_lshlrev_b32_e32 v38, 16, v218
	v_and_b32_e32 v39, 0xffff0000, v218
	v_pk_mul_f32 v[28:29], v[28:29], v[38:39]
	v_lshl_add_u64 v[56:57], v[56:57], 0, v[142:143]
	v_cvt_pk_bf16_f32 v38, v28, v29
	v_lshlrev_b32_e32 v28, 16, v219
	v_and_b32_e32 v29, 0xffff0000, v219
	v_pk_mul_f32 v[28:29], v[30:31], v[28:29]
	s_waitcnt vmcnt(11)
	v_lshlrev_b32_e32 v30, 16, v221
	v_cvt_pk_bf16_f32 v39, v28, v29
	v_lshlrev_b32_e32 v28, 16, v220
	v_and_b32_e32 v29, 0xffff0000, v220
	v_and_b32_e32 v31, 0xffff0000, v221
	v_pk_mul_f32 v[28:29], v[32:33], v[28:29]
	v_pk_mul_f32 v[30:31], v[34:35], v[30:31]
	v_cvt_pk_bf16_f32 v28, v28, v29
	v_cvt_pk_bf16_f32 v29, v30, v31
	v_lshlrev_b32_e32 v30, 16, v222
	v_and_b32_e32 v31, 0xffff0000, v222
	v_pk_mul_f32 v[24:25], v[24:25], v[30:31]
	global_store_dwordx4 v[56:57], v[52:55], off offset:256
	v_cvt_pk_bf16_f32 v30, v24, v25
	v_lshlrev_b32_e32 v24, 16, v223
	v_and_b32_e32 v25, 0xffff0000, v223
	v_pk_mul_f32 v[24:25], v[26:27], v[24:25]
	s_waitcnt vmcnt(11)
	v_lshlrev_b32_e32 v26, 16, v224
	v_and_b32_e32 v27, 0xffff0000, v224
	v_pk_mul_f32 v[20:21], v[20:21], v[26:27]
	v_lshlrev_b32_e32 v26, 16, v225
	v_and_b32_e32 v27, 0xffff0000, v225
	v_pk_mul_f32 v[22:23], v[22:23], v[26:27]
	v_cvt_pk_bf16_f32 v20, v20, v21
	v_cvt_pk_bf16_f32 v21, v22, v23
	v_lshlrev_b32_e32 v22, 16, v226
	v_and_b32_e32 v23, 0xffff0000, v226
	v_pk_mul_f32 v[12:13], v[12:13], v[22:23]
	v_lshlrev_b64 v[52:53], 11, v[98:99]
	v_cvt_pk_bf16_f32 v22, v12, v13
	v_lshlrev_b32_e32 v12, 16, v227
	v_and_b32_e32 v13, 0xffff0000, v227
	v_pk_mul_f32 v[12:13], v[14:15], v[12:13]
	s_waitcnt vmcnt(10)
	v_lshlrev_b32_e32 v14, 16, v229
	v_cvt_pk_bf16_f32 v23, v12, v13
	v_lshlrev_b32_e32 v12, 16, v228
	v_and_b32_e32 v13, 0xffff0000, v228
	v_and_b32_e32 v15, 0xffff0000, v229
	v_pk_mul_f32 v[12:13], v[16:17], v[12:13]
	v_pk_mul_f32 v[14:15], v[18:19], v[14:15]
	v_cvt_pk_bf16_f32 v12, v12, v13
	v_cvt_pk_bf16_f32 v13, v14, v15
	v_lshlrev_b32_e32 v14, 16, v230
	v_and_b32_e32 v15, 0xffff0000, v230
	v_pk_mul_f32 v[8:9], v[8:9], v[14:15]
	v_cvt_pk_bf16_f32 v47, v40, v41
	v_cvt_pk_bf16_f32 v14, v8, v9
	v_lshlrev_b32_e32 v8, 16, v231
	v_and_b32_e32 v9, 0xffff0000, v231
	v_lshl_add_u64 v[40:41], s[4:5], 0, v[52:53]
	v_pk_mul_f32 v[8:9], v[10:11], v[8:9]
	s_waitcnt vmcnt(9)
	v_lshlrev_b32_e32 v10, 16, v232
	v_and_b32_e32 v11, 0xffff0000, v232
	v_lshl_add_u64 v[40:41], v[40:41], 0, v[142:143]
	v_pk_mul_f32 v[4:5], v[4:5], v[10:11]
	v_lshlrev_b32_e32 v10, 16, v233
	v_and_b32_e32 v11, 0xffff0000, v233
	global_store_dwordx4 v[40:41], v[36:39], off offset:256
	v_pk_mul_f32 v[6:7], v[6:7], v[10:11]
	v_cvt_pk_bf16_f32 v31, v24, v25
	v_lshlrev_b64 v[36:37], 11, v[100:101]
	v_lshl_add_u64 v[24:25], s[4:5], 0, v[36:37]
	v_cvt_pk_bf16_f32 v4, v4, v5
	v_cvt_pk_bf16_f32 v5, v6, v7
	v_lshlrev_b32_e32 v6, 16, v234
	v_and_b32_e32 v7, 0xffff0000, v234
	v_lshl_add_u64 v[24:25], v[24:25], 0, v[142:143]
	v_pk_mul_f32 v[0:1], v[0:1], v[6:7]
	global_store_dwordx4 v[24:25], v[20:23], off offset:256
	v_cvt_pk_bf16_f32 v6, v0, v1
	v_lshlrev_b32_e32 v0, 16, v235
	v_lshlrev_b64 v[20:21], 11, v[136:137]
	v_and_b32_e32 v1, 0xffff0000, v235
	v_cvt_pk_bf16_f32 v15, v8, v9
	v_lshl_add_u64 v[8:9], s[4:5], 0, v[20:21]
	v_pk_mul_f32 v[0:1], v[2:3], v[0:1]
	v_lshl_add_u64 v[8:9], v[8:9], 0, v[142:143]
	v_cvt_pk_bf16_f32 v7, v0, v1
	global_store_dwordx4 v[56:57], v[60:63], off
	global_store_dwordx4 v[40:41], v[44:47], off
	global_store_dwordx4 v[24:25], v[28:31], off
	global_store_dwordx4 v[8:9], v[12:15], off
	global_store_dwordx4 v[8:9], v[4:7], off offset:256
	s_cbranch_vccnz .LBB0_482
	s_andn2_b64 vcc, exec, s[10:11]
	s_cbranch_vccnz .LBB0_481
	s_barrier
	s_branch .LBB0_481
